# v16 + FFN-up stagger refined: the 8-tile CUs start 1..4 sleep units late by (bx>>3)&3 (four sub-groups) instead of one group
# baseline (speedup 1.0000x reference)
; __global__ void __launch_bounds__(512, 2) fwd(Args args) {
;     ...
;     if (IN(7)) { pg8::Gemm g{Xb, Wt_up, M, FF, DM, DM}; pg8::StaticOrder S; S.init(M, FF, G, bx); pg8::EpiBf16<2> E{Ub, FF};
;         pg8::gemm_phase<pg8::EpiBf16<2>, pg8::StaticOrder, true, true>(lds, g, S, E); }
.LBB0_1009:
	s_cmp_lt_i32 s78, 8
	s_cselect_b64 s[0:1], -1, 0
	s_and_b64 s[0:1], s[0:1], s[4:5]
	s_andn2_b64 vcc, exec, s[0:1]
	s_cbranch_vccnz .LBB0_1026
	s_cmpk_lg_i32 s96, 0x100
	s_cbranch_scc1 .Lstg7_done
	s_cmpk_lt_i32 s74, 0x80
	s_cbranch_scc1 .Lstg7_done
	s_lshr_b32 s2, s74, 3
	s_and_b32 s2, s2, 3
	s_add_u32 s2, s2, 1
.Lstg7_loop:
	s_sleep 127
	s_sub_u32 s2, s2, 1
	s_cmp_lg_u32 s2, 0
	s_cbranch_scc1 .Lstg7_loop

; __global__ void __launch_bounds__(512, 2) fwd(Args args) {
;     ...
;     if (IN(14)) { pg8::Gemm g{Xb, Wt_up + (size_t)DM * FF, M, FF, DM, DM}; pg8::StaticOrder S; S.init(M, FF, G, bx); pg8::EpiBf16<2> E{Ub, FF};
;         pg8::gemm_phase<pg8::EpiBf16<2>, pg8::StaticOrder, true, true>(lds, g, S, E); }
.LBB0_1614:
	s_cmp_lt_i32 s78, 15
	s_cselect_b64 s[0:1], -1, 0
	s_and_b64 s[0:1], s[0:1], s[4:5]
	s_andn2_b64 vcc, exec, s[0:1]
	s_cbranch_vccnz .LBB0_1631
	s_cmpk_lg_i32 s96, 0x100
	s_cbranch_scc1 .Lstg14_done
	s_cmpk_lt_i32 s74, 0x80
	s_cbranch_scc1 .Lstg14_done
	s_lshr_b32 s2, s74, 3
	s_and_b32 s2, s2, 3
	s_add_u32 s2, s2, 1
